# v80 + mLSTM scan: quad reductions via DPP quad_perm, loop-invariant LDS reads (decay weights, per-row max) read once per chunk instead of per step
# speedup vs baseline: 1.0085x; 1.0011x over previous
.LBB0_208:
	s_waitcnt lgkmcnt(0)
	s_barrier
	s_waitcnt vmcnt(13)
	ds_write_b128 v189, v[0:3]
	s_waitcnt vmcnt(12)
	ds_write_b128 v189, v[4:7] offset:34816
	s_waitcnt vmcnt(11)
	v_alignbit_b32 v72, v9, v9, 16
	v_alignbit_b32 v73, v8, v8, 16
	v_cndmask_b32_e64 v80, v73, v11, s[2:3]
	v_cndmask_b32_e64 v81, v72, v10, s[2:3]
	ds_read_b128 v[72:75], v156
	v_alignbit_b32 v76, v11, v11, 16
	v_cndmask_b32_e64 v83, v76, v8, s[2:3]
	v_alignbit_b32 v77, v10, v10, 16
	v_lshlrev_b32_e32 v84, 16, v83
	v_and_b32_e32 v83, 0xffff0000, v83
	v_cndmask_b32_e64 v82, v77, v9, s[2:3]
	ds_read_b128 v[76:79], v156 offset:16
	ds_read_b128 v[246:249], v156
	ds_read_b128 v[250:253], v156 offset:16
	s_waitcnt lgkmcnt(1)
	v_mul_f32_e32 v72, v72, v84
	v_mul_f32_e32 v73, v73, v83
	v_cvt_pk_bf16_f32 v72, v72, v73
	v_lshlrev_b32_e32 v73, 16, v82
	v_mul_f32_e32 v73, v74, v73
	v_and_b32_e32 v74, 0xffff0000, v82
	v_mul_f32_e32 v74, v75, v74
	v_cvt_pk_bf16_f32 v73, v73, v74
	v_lshlrev_b32_e32 v74, 16, v81
	v_and_b32_e32 v75, 0xffff0000, v81
	s_waitcnt lgkmcnt(0)
	v_mul_f32_e32 v74, v76, v74
	v_mul_f32_e32 v75, v77, v75
	v_cvt_pk_bf16_f32 v74, v74, v75
	v_lshlrev_b32_e32 v75, 16, v80
	v_mul_f32_e32 v75, v78, v75
	v_and_b32_e32 v76, 0xffff0000, v80
	v_mul_f32_e32 v76, v79, v76
	v_cvt_pk_bf16_f32 v75, v75, v76
	ds_write_b128 v190, v[72:75]
	s_waitcnt vmcnt(10)
	ds_write_b128 v192, v[12:15]
	s_waitcnt vmcnt(9)
	ds_write_b128 v192, v[16:19] offset:34816
	s_waitcnt vmcnt(8)
	v_alignbit_b32 v72, v21, v21, 16
	v_alignbit_b32 v73, v20, v20, 16
	v_cndmask_b32_e64 v80, v73, v23, s[2:3]
	v_cndmask_b32_e64 v81, v72, v22, s[2:3]
	v_mov_b32_e32 v72, v246
	v_mov_b32_e32 v73, v247
	v_mov_b32_e32 v74, v248
	v_mov_b32_e32 v75, v249
	v_alignbit_b32 v76, v23, v23, 16
	v_cndmask_b32_e64 v83, v76, v20, s[2:3]
	v_alignbit_b32 v77, v22, v22, 16
	v_lshlrev_b32_e32 v84, 16, v83
	v_and_b32_e32 v83, 0xffff0000, v83
	v_cndmask_b32_e64 v82, v77, v21, s[2:3]
	v_mov_b32_e32 v76, v250
	v_mov_b32_e32 v77, v251
	v_mov_b32_e32 v78, v252
	v_mov_b32_e32 v79, v253
	s_nop 0
	v_mul_f32_e32 v72, v72, v84
	v_mul_f32_e32 v73, v73, v83
	v_cvt_pk_bf16_f32 v72, v72, v73
	v_lshlrev_b32_e32 v73, 16, v82
	v_mul_f32_e32 v73, v74, v73
	v_and_b32_e32 v74, 0xffff0000, v82
	v_mul_f32_e32 v74, v75, v74
	v_cvt_pk_bf16_f32 v73, v73, v74
	v_lshlrev_b32_e32 v74, 16, v81
	v_and_b32_e32 v75, 0xffff0000, v81
	s_nop 0
	v_mul_f32_e32 v74, v76, v74
	v_mul_f32_e32 v75, v77, v75
	v_cvt_pk_bf16_f32 v74, v74, v75
	v_lshlrev_b32_e32 v75, 16, v80
	v_mul_f32_e32 v75, v78, v75
	v_and_b32_e32 v76, 0xffff0000, v80
	v_mul_f32_e32 v76, v79, v76
	v_cvt_pk_bf16_f32 v75, v75, v76
	ds_write_b128 v193, v[72:75]
	s_waitcnt vmcnt(7)
	ds_write_b128 v194, v[24:27]
	s_waitcnt vmcnt(6)
	ds_write_b128 v194, v[28:31] offset:34816
	s_waitcnt vmcnt(5)
	v_alignbit_b32 v72, v33, v33, 16
	v_alignbit_b32 v73, v32, v32, 16
	v_cndmask_b32_e64 v80, v73, v35, s[2:3]
	v_cndmask_b32_e64 v81, v72, v34, s[2:3]
	v_mov_b32_e32 v72, v246
	v_mov_b32_e32 v73, v247
	v_mov_b32_e32 v74, v248
	v_mov_b32_e32 v75, v249
	v_alignbit_b32 v76, v35, v35, 16
	v_cndmask_b32_e64 v83, v76, v32, s[2:3]
	v_alignbit_b32 v77, v34, v34, 16
	v_lshlrev_b32_e32 v84, 16, v83
	v_and_b32_e32 v83, 0xffff0000, v83
	v_cndmask_b32_e64 v82, v77, v33, s[2:3]
	v_mov_b32_e32 v76, v250
	v_mov_b32_e32 v77, v251
	v_mov_b32_e32 v78, v252
	v_mov_b32_e32 v79, v253
	s_nop 0
	v_mul_f32_e32 v72, v72, v84
	v_mul_f32_e32 v73, v73, v83
	v_cvt_pk_bf16_f32 v72, v72, v73
	v_lshlrev_b32_e32 v73, 16, v82
	v_mul_f32_e32 v73, v74, v73
	v_and_b32_e32 v74, 0xffff0000, v82
	v_mul_f32_e32 v74, v75, v74
	v_cvt_pk_bf16_f32 v73, v73, v74
	v_lshlrev_b32_e32 v74, 16, v81
	v_and_b32_e32 v75, 0xffff0000, v81
	s_nop 0
	v_mul_f32_e32 v74, v76, v74
	v_mul_f32_e32 v75, v77, v75
	v_cvt_pk_bf16_f32 v74, v74, v75
	v_lshlrev_b32_e32 v75, 16, v80
	v_mul_f32_e32 v75, v78, v75
	v_and_b32_e32 v76, 0xffff0000, v80
	v_mul_f32_e32 v76, v79, v76
	v_cvt_pk_bf16_f32 v75, v75, v76
	ds_write_b128 v195, v[72:75]
	s_waitcnt vmcnt(4)
	ds_write_b128 v196, v[36:39]
	s_waitcnt vmcnt(3)
	ds_write_b128 v196, v[40:43] offset:34816
	s_waitcnt vmcnt(2)
	v_alignbit_b32 v72, v45, v45, 16
	v_alignbit_b32 v73, v44, v44, 16
	v_cndmask_b32_e64 v80, v73, v47, s[2:3]
	v_cndmask_b32_e64 v81, v72, v46, s[2:3]
	v_mov_b32_e32 v72, v246
	v_mov_b32_e32 v73, v247
	v_mov_b32_e32 v74, v248
	v_mov_b32_e32 v75, v249
	v_alignbit_b32 v76, v47, v47, 16
	v_cndmask_b32_e64 v83, v76, v44, s[2:3]
	v_alignbit_b32 v77, v46, v46, 16
	v_lshlrev_b32_e32 v84, 16, v83
	v_and_b32_e32 v83, 0xffff0000, v83
	v_cndmask_b32_e64 v82, v77, v45, s[2:3]
	v_mov_b32_e32 v76, v250
	v_mov_b32_e32 v77, v251
	v_mov_b32_e32 v78, v252
	v_mov_b32_e32 v79, v253
	s_nop 0
	v_mul_f32_e32 v72, v72, v84
	v_mul_f32_e32 v73, v73, v83
	v_cvt_pk_bf16_f32 v72, v72, v73
	v_lshlrev_b32_e32 v73, 16, v82
	v_mul_f32_e32 v73, v74, v73
	v_and_b32_e32 v74, 0xffff0000, v82
	v_mul_f32_e32 v74, v75, v74
	v_cvt_pk_bf16_f32 v73, v73, v74
	v_lshlrev_b32_e32 v74, 16, v81
	v_and_b32_e32 v75, 0xffff0000, v81
	s_nop 0
	v_mul_f32_e32 v74, v76, v74
	v_mul_f32_e32 v75, v77, v75
	v_cvt_pk_bf16_f32 v74, v74, v75
	v_lshlrev_b32_e32 v75, 16, v80
	v_mul_f32_e32 v75, v78, v75
	v_and_b32_e32 v76, 0xffff0000, v80
	v_mul_f32_e32 v76, v79, v76
	v_cvt_pk_bf16_f32 v75, v75, v76
	ds_write_b128 v197, v[72:75]
	s_waitcnt vmcnt(1)
	v_alignbit_b32 v72, v51, v51, 16
	v_alignbit_b32 v73, v50, v50, 16
	v_alignbit_b32 v74, v49, v49, 16
	v_alignbit_b32 v75, v48, v48, 16
	v_cndmask_b32_e64 v75, v75, v51, s[2:3]
	v_cndmask_b32_e64 v74, v74, v50, s[2:3]
	v_cndmask_b32_e64 v73, v73, v49, s[2:3]
	v_cndmask_b32_e64 v72, v72, v48, s[2:3]
	v_add_u32_e32 v76, v168, v188
	ds_write_b128 v76, v[72:75]
	s_waitcnt vmcnt(0)
	v_alignbit_b32 v72, v55, v55, 16
	v_alignbit_b32 v73, v54, v54, 16
	v_alignbit_b32 v74, v53, v53, 16
	v_alignbit_b32 v75, v52, v52, 16
	v_cndmask_b32_e64 v75, v75, v55, s[2:3]
	v_cndmask_b32_e64 v74, v74, v54, s[2:3]
	v_cndmask_b32_e64 v73, v73, v53, s[2:3]
	v_cndmask_b32_e64 v72, v72, v52, s[2:3]
	v_add_u32_e32 v76, v168, v191
	v_mov_b32_e32 v88, 0
	ds_write_b128 v76, v[72:75]
	s_mov_b32 s85, 0
	v_mov_b32_e32 v89, v88
	v_mov_b32_e32 v90, v88
	v_mov_b32_e32 v91, v88
	v_mov_b32_e32 v92, v88
	v_mov_b32_e32 v93, v88
	v_mov_b32_e32 v94, v88
	v_mov_b32_e32 v95, v88
	v_mov_b32_e32 v100, v88
	v_mov_b32_e32 v101, v88
	v_mov_b32_e32 v102, v88
	v_mov_b32_e32 v103, v88
	v_mov_b32_e32 v108, v88
	v_mov_b32_e32 v109, v88
	v_mov_b32_e32 v110, v88
	v_mov_b32_e32 v111, v88
	v_mov_b32_e32 v96, v88
	v_mov_b32_e32 v97, v88
	v_mov_b32_e32 v98, v88
	v_mov_b32_e32 v99, v88
	v_mov_b32_e32 v104, v88
	v_mov_b32_e32 v105, v88
	v_mov_b32_e32 v106, v88
	v_mov_b32_e32 v107, v88
	v_mov_b32_e32 v112, v88
	v_mov_b32_e32 v113, v88
	v_mov_b32_e32 v114, v88
	v_mov_b32_e32 v115, v88
	v_mov_b32_e32 v116, v88
	v_mov_b32_e32 v117, v88
	v_mov_b32_e32 v118, v88
	v_mov_b32_e32 v119, v88
	v_mov_b32_e32 v72, v88
	v_mov_b32_e32 v73, v88
	v_mov_b32_e32 v74, v88
	v_mov_b32_e32 v75, v88
	v_mov_b32_e32 v76, v88
	v_mov_b32_e32 v77, v88
	v_mov_b32_e32 v78, v88
	v_mov_b32_e32 v79, v88
	v_mov_b32_e32 v80, v88
	v_mov_b32_e32 v81, v88
	v_mov_b32_e32 v82, v88
	v_mov_b32_e32 v83, v88
	v_mov_b32_e32 v84, v88
	v_mov_b32_e32 v85, v88
	v_mov_b32_e32 v86, v88
	v_mov_b32_e32 v87, v88
	s_waitcnt lgkmcnt(0)
	s_barrier
	s_add_i32 s99, s84, 1
	s_cmp_ge_u32 s99, s95
	s_cbranch_scc1 .Lpf_skip
	s_lshl_b32 s100, s99, 7
	s_sub_i32 s101, s94, s100
	s_and_b64 s[86:87], s[2:3], exec
	s_cselect_b32 s100, s100, s101
	s_add_i32 s100, s100, s89
	s_ashr_i32 s101, s100, 7
	v_add_u32_e32 v0, s100, v148
	v_add_u32_e32 v12, s100, v150
	v_add_u32_e32 v24, s100, v151
	v_add_u32_e32 v36, s100, v152
	v_ashrrev_i32_e32 v1, 31, v0
	v_mad_i64_i32 v[8:9], s[86:87], s101, v149, v[136:137]
	v_ashrrev_i32_e32 v13, 31, v12
	v_mad_i64_i32 v[20:21], s[86:87], s101, v149, v[138:139]
	v_ashrrev_i32_e32 v25, 31, v24
	v_mad_i64_i32 v[32:33], s[86:87], s101, v149, v[140:141]
	v_ashrrev_i32_e32 v37, 31, v36
	v_mad_i64_i32 v[46:47], s[86:87], s101, v149, v[142:143]
	v_lshlrev_b64 v[0:1], 8, v[0:1]
	v_lshlrev_b64 v[44:45], 8, v[8:9]
	v_lshlrev_b64 v[12:13], 8, v[12:13]
	v_lshlrev_b64 v[52:53], 8, v[20:21]
	v_lshlrev_b64 v[24:25], 8, v[24:25]
	v_lshlrev_b64 v[32:33], 8, v[32:33]
	v_lshlrev_b64 v[36:37], 8, v[36:37]
	v_lshlrev_b64 v[46:47], 8, v[46:47]
	v_lshl_add_u64 v[2:3], v[128:129], 0, v[0:1]
	v_lshl_add_u64 v[4:5], v[130:131], 0, v[0:1]
	v_lshl_add_u64 v[8:9], v[132:133], 0, v[44:45]
	v_lshl_add_u64 v[14:15], v[128:129], 0, v[12:13]
	v_lshl_add_u64 v[16:17], v[130:131], 0, v[12:13]
	v_lshl_add_u64 v[20:21], v[132:133], 0, v[52:53]
	v_lshl_add_u64 v[26:27], v[128:129], 0, v[24:25]
	v_lshl_add_u64 v[28:29], v[130:131], 0, v[24:25]
	v_lshl_add_u64 v[32:33], v[132:133], 0, v[32:33]
	v_lshl_add_u64 v[38:39], v[128:129], 0, v[36:37]
	v_lshl_add_u64 v[40:41], v[130:131], 0, v[36:37]
	v_lshl_add_u64 v[46:47], v[132:133], 0, v[46:47]
	v_lshl_add_u64 v[48:49], v[144:145], 0, v[44:45]
	v_lshl_add_u64 v[52:53], v[144:145], 0, v[52:53]
	global_load_dwordx4 v[0:3], v[2:3], off
	s_nop 0
	global_load_dwordx4 v[4:7], v[4:5], off
	s_nop 0
	global_load_dwordx4 v[8:11], v[8:9], off
	s_nop 0
	global_load_dwordx4 v[12:15], v[14:15], off
	s_nop 0
	global_load_dwordx4 v[16:19], v[16:17], off
	s_nop 0
	global_load_dwordx4 v[20:23], v[20:21], off
	s_nop 0
	global_load_dwordx4 v[24:27], v[26:27], off
	s_nop 0
	global_load_dwordx4 v[28:31], v[28:29], off
	s_nop 0
	global_load_dwordx4 v[32:35], v[32:33], off
	s_nop 0
	global_load_dwordx4 v[36:39], v[38:39], off
	s_nop 0
	global_load_dwordx4 v[40:43], v[40:41], off
	s_nop 0
	global_load_dwordx4 v[44:47], v[46:47], off
	s_nop 0
	global_load_dwordx4 v[48:51], v[48:49], off
	s_nop 0
	global_load_dwordx4 v[52:55], v[52:53], off
	s_and_saveexec_b64 s[86:87], s[0:1]
	s_cbranch_execz .Lpf_215
	v_add_u32_e32 v120, s100, v153
	s_waitcnt lgkmcnt(0)
	v_ashrrev_i32_e32 v121, 31, v120
	v_readlane_b32 s100, v255, 10
	v_lshlrev_b64 v[120:121], 6, v[120:121]
	v_readlane_b32 s101, v255, 11
	s_nop 1
	v_lshl_add_u64 v[120:121], s[100:101], 0, v[120:121]
	global_load_dword v154, v[120:121], off
	global_load_dword v155, v[120:121], off offset:16

.Lpf_skip:
.LBB0_209:
	v_add_u32_e32 v202, s85, v214
	v_add_u32_e32 v219, s85, v213
	ds_read_b128 v[120:123], v202 offset:34816
	ds_read_b128 v[124:127], v219
	ds_read_b128 v[220:223], v219 offset:4352
	ds_read_b128 v[224:227], v219 offset:8704
	ds_read_b128 v[228:231], v219 offset:13056
	ds_read_b128 v[232:235], v202
	v_add_u32_e32 v236, s85, v212
	v_add_u32_e32 v219, 0x1dc00, v236
	v_add_u32_e32 v236, 0x1ed00, v236
	s_waitcnt lgkmcnt(4)
	v_mfma_f32_16x16x32_bf16 v[116:119], v[120:123], v[124:127], v[116:119]
	ds_read_b128 v[236:239], v236
	s_add_i32 s85, s85, 64
	s_cmpk_eq_i32 s85, 0x100
	s_waitcnt lgkmcnt(4)
	v_mfma_f32_16x16x32_bf16 v[112:115], v[120:123], v[220:223], v[112:115]
	s_waitcnt lgkmcnt(3)
	v_mfma_f32_16x16x32_bf16 v[104:107], v[120:123], v[224:227], v[104:107]
	s_waitcnt lgkmcnt(2)
	v_mfma_f32_16x16x32_bf16 v[96:99], v[120:123], v[228:231], v[96:99]
	ds_read_b128 v[120:123], v219
	s_waitcnt lgkmcnt(0)
	v_mfma_f32_16x16x32_bf16 v[84:87], v[232:235], v[120:123], v[84:87]
	v_mfma_f32_16x16x32_bf16 v[80:83], v[232:235], v[236:239], v[80:83]
	ds_read_b128 v[232:235], v202 offset:39168
	s_waitcnt lgkmcnt(0)
	v_mfma_f32_16x16x32_bf16 v[108:111], v[232:235], v[124:127], v[108:111]
	ds_read_b128 v[124:127], v202 offset:4352
	v_mfma_f32_16x16x32_bf16 v[100:103], v[232:235], v[220:223], v[100:103]
	v_mfma_f32_16x16x32_bf16 v[92:95], v[232:235], v[224:227], v[92:95]
	v_mfma_f32_16x16x32_bf16 v[88:91], v[232:235], v[228:231], v[88:91]
	s_waitcnt lgkmcnt(0)
	v_mfma_f32_16x16x32_bf16 v[76:79], v[124:127], v[120:123], v[76:79]
	v_mfma_f32_16x16x32_bf16 v[72:75], v[124:127], v[236:239], v[72:75]
	s_cbranch_scc0 .LBB0_209
	ds_read_b128 v[120:123], v169
	ds_read_b128 v[124:127], v169 offset:16
	ds_read_b128 v[220:223], v169 offset:32
	ds_read_b128 v[224:227], v169 offset:48
	ds_read_b128 v[228:231], v170
	ds_read_b128 v[232:235], v170 offset:16
	ds_read_b128 v[236:239], v170 offset:32
	ds_read_b128 v[240:243], v170 offset:48
	s_waitcnt lgkmcnt(7)
	v_lshlrev_b32_e32 v202, 16, v120
	v_and_b32_e32 v120, 0xffff0000, v120
	s_waitcnt lgkmcnt(3)
	v_mul_f32_e32 v120, v229, v120
	v_fmac_f32_e32 v120, v228, v202
	v_lshlrev_b32_e32 v202, 16, v121
	v_fmac_f32_e32 v120, v230, v202
	v_and_b32_e32 v121, 0xffff0000, v121
	v_fmac_f32_e32 v120, v231, v121
	v_lshlrev_b32_e32 v121, 16, v122
	s_waitcnt lgkmcnt(2)
	v_fmac_f32_e32 v120, v232, v121
	v_and_b32_e32 v121, 0xffff0000, v122
	v_fmac_f32_e32 v120, v233, v121
	v_lshlrev_b32_e32 v121, 16, v123
	v_fmac_f32_e32 v120, v234, v121
	v_and_b32_e32 v121, 0xffff0000, v123
	v_fmac_f32_e32 v120, v235, v121
	v_and_b32_e32 v121, 0xffff0000, v124
	v_add_f32_e32 v202, 0, v120
	v_lshlrev_b32_e32 v120, 16, v124
	s_waitcnt lgkmcnt(1)
	v_mul_f32_e32 v124, v237, v121
	v_fmac_f32_e32 v124, v236, v120
	v_lshlrev_b32_e32 v120, 16, v125
	v_fmac_f32_e32 v124, v238, v120
	v_and_b32_e32 v120, 0xffff0000, v125
	v_fmac_f32_e32 v124, v239, v120
	v_lshlrev_b32_e32 v120, 16, v126
	s_waitcnt lgkmcnt(0)
	v_fmac_f32_e32 v124, v240, v120
	v_and_b32_e32 v120, 0xffff0000, v126
	v_fmac_f32_e32 v124, v241, v120
	v_lshlrev_b32_e32 v120, 16, v127
	v_fmac_f32_e32 v124, v242, v120
	v_and_b32_e32 v120, 0xffff0000, v127
	v_fmac_f32_e32 v124, v243, v120
	ds_read_b128 v[120:123], v170 offset:64
	v_add_f32_e32 v202, v202, v124
	ds_read_b128 v[124:127], v170 offset:80
	v_lshlrev_b32_e32 v219, 16, v220
	v_and_b32_e32 v220, 0xffff0000, v220
	s_waitcnt lgkmcnt(1)
	v_mul_f32_e32 v220, v121, v220
	v_fmac_f32_e32 v220, v120, v219
	v_lshlrev_b32_e32 v120, 16, v221
	v_fmac_f32_e32 v220, v122, v120
	v_and_b32_e32 v120, 0xffff0000, v221
	v_fmac_f32_e32 v220, v123, v120
	v_lshlrev_b32_e32 v120, 16, v222
	s_waitcnt lgkmcnt(0)
	v_fmac_f32_e32 v220, v124, v120
	v_and_b32_e32 v120, 0xffff0000, v222
	v_fmac_f32_e32 v220, v125, v120
	v_lshlrev_b32_e32 v120, 16, v223
	v_fmac_f32_e32 v220, v126, v120
	v_and_b32_e32 v120, 0xffff0000, v223
	v_fmac_f32_e32 v220, v127, v120
	ds_read_b128 v[120:123], v170 offset:96
	ds_read_b128 v[124:127], v170 offset:112
	v_add_f32_e32 v202, v202, v220
	v_and_b32_e32 v220, 0xffff0000, v224
	v_lshlrev_b32_e32 v219, 16, v224
	s_waitcnt lgkmcnt(1)
	v_mul_f32_e32 v121, v121, v220
	v_fmac_f32_e32 v121, v120, v219
	v_lshlrev_b32_e32 v120, 16, v225
	v_fmac_f32_e32 v121, v122, v120
	v_and_b32_e32 v120, 0xffff0000, v225
	v_fmac_f32_e32 v121, v123, v120
	v_lshlrev_b32_e32 v120, 16, v226
	s_waitcnt lgkmcnt(0)
	v_fmac_f32_e32 v121, v124, v120
	v_and_b32_e32 v120, 0xffff0000, v226
	v_fmac_f32_e32 v121, v125, v120
	v_lshlrev_b32_e32 v120, 16, v227
	v_fmac_f32_e32 v121, v126, v120
	v_and_b32_e32 v120, 0xffff0000, v227
	v_fmac_f32_e32 v121, v127, v120
	v_add_f32_e32 v120, v202, v121
	s_nop 1
	v_add_f32_dpp v120, v120, v120 quad_perm:[1,0,3,2] row_mask:0xf bank_mask:0xf
	s_waitcnt lgkmcnt(0)
	s_nop 1
	v_add_f32_dpp v120, v120, v120 quad_perm:[2,3,0,1] row_mask:0xf bank_mask:0xf
	s_and_saveexec_b64 s[86:87], s[6:7]
	s_cbranch_execz .LBB0_212
	s_waitcnt lgkmcnt(0)
	s_nop 0
	ds_write_b32 v173, v120

.LBB0_216:
	v_add_u32_e32 v120, s96, v174
	ds_read_b128 v[124:127], v120
	ds_read_b32 v202, v198
	ds_read_b32 v246, v209
	ds_read_b32 v247, v210
	ds_read_b32 v248, v211
	s_waitcnt lgkmcnt(0)
	v_sub_f32_e32 v121, v124, v202
	v_sub_f32_e32 v122, v125, v202
	v_mul_f32_e32 v121, 0x3fb8aa3b, v121
	v_mul_f32_e32 v122, 0x3fb8aa3b, v122
	v_exp_f32_e32 v219, v121
	v_exp_f32_e32 v220, v122
	ds_read_b128 v[120:123], v120 offset:64
	v_sub_f32_e32 v221, v126, v202
	v_mul_f32_e32 v221, 0x3fb8aa3b, v221
	v_sub_f32_e32 v222, v127, v202
	v_exp_f32_e32 v221, v221
	v_mul_f32_e32 v222, 0x3fb8aa3b, v222
	s_waitcnt lgkmcnt(0)
	v_sub_f32_e32 v223, v120, v202
	v_exp_f32_e32 v222, v222
	v_mul_f32_e32 v223, 0x3fb8aa3b, v223
	v_sub_f32_e32 v224, v121, v202
	v_cndmask_b32_e64 v219, v219, 0, s[18:19]
	v_exp_f32_e32 v223, v223
	v_mul_f32_e32 v224, 0x3fb8aa3b, v224
	v_sub_f32_e32 v225, v122, v202
	v_cndmask_b32_e64 v220, 0, v220, s[20:21]
	v_fma_f32 v227, v116, v219, 0
	v_exp_f32_e32 v224, v224
	v_mul_f32_e32 v225, 0x3fb8aa3b, v225
	v_sub_f32_e32 v202, v123, v202
	v_fmac_f32_e32 v227, v117, v220
	v_cndmask_b32_e64 v221, v221, 0, s[22:23]
	v_exp_f32_e32 v225, v225
	v_mul_f32_e32 v202, 0x3fb8aa3b, v202
	v_fmac_f32_e32 v227, v118, v221
	v_cndmask_b32_e64 v222, v222, 0, s[24:25]
	v_exp_f32_e32 v202, v202
	v_fmac_f32_e32 v227, v119, v222
	v_cndmask_b32_e64 v223, v223, 0, s[26:27]
	v_fmac_f32_e32 v227, v108, v223
	v_cndmask_b32_e64 v224, v224, 0, s[28:29]
	v_fmac_f32_e32 v227, v109, v224
	v_cndmask_b32_e64 v225, v225, 0, s[30:31]
	v_fmac_f32_e32 v227, v110, v225
	v_cndmask_b32_e64 v226, v202, 0, s[34:35]
	v_fmac_f32_e32 v227, v111, v226
	v_mov_b32_e32 v202, v227
	s_nop 1
	v_permlane16_swap_b32_e32 v227, v202
	v_add_f32_e32 v227, v227, v202
	v_mov_b32_e32 v228, v227
	s_nop 1
	v_permlane32_swap_b32_e32 v227, v228
	s_and_saveexec_b64 s[86:87], s[8:9]
	s_cbranch_execz .LBB0_218
	v_add_f32_e32 v202, v227, v228
	ds_write_b32 v199, v202
.LBB0_218:
	s_or_b64 exec, exec, s[86:87]
	v_mov_b32_e32 v202, v246
	s_nop 0
	v_sub_f32_e32 v227, v124, v202
	v_sub_f32_e32 v228, v125, v202
	v_mul_f32_e32 v227, 0x3fb8aa3b, v227
	v_sub_f32_e32 v229, v126, v202
	v_mul_f32_e32 v228, 0x3fb8aa3b, v228
	v_exp_f32_e32 v227, v227
	v_exp_f32_e32 v228, v228
	v_mul_f32_e32 v229, 0x3fb8aa3b, v229
	v_sub_f32_e32 v230, v127, v202
	v_exp_f32_e32 v229, v229
	v_mul_f32_e32 v230, 0x3fb8aa3b, v230
	v_sub_f32_e32 v231, v120, v202
	v_exp_f32_e32 v230, v230
	v_mul_f32_e32 v231, 0x3fb8aa3b, v231
	v_sub_f32_e32 v232, v121, v202
	v_cndmask_b32_e64 v227, v227, 0, s[36:37]
	v_exp_f32_e32 v231, v231
	v_mul_f32_e32 v232, 0x3fb8aa3b, v232
	v_sub_f32_e32 v233, v122, v202
	v_cndmask_b32_e64 v228, 0, v228, s[38:39]
	v_fma_f32 v235, v112, v227, 0
	v_exp_f32_e32 v232, v232
	v_mul_f32_e32 v233, 0x3fb8aa3b, v233
	v_sub_f32_e32 v202, v123, v202
	v_fmac_f32_e32 v235, v113, v228
	v_cndmask_b32_e64 v229, v229, 0, s[40:41]
	v_exp_f32_e32 v233, v233
	v_mul_f32_e32 v202, 0x3fb8aa3b, v202
	v_fmac_f32_e32 v235, v114, v229
	v_cndmask_b32_e64 v230, v230, 0, s[42:43]
	v_exp_f32_e32 v202, v202
	v_fmac_f32_e32 v235, v115, v230
	v_cndmask_b32_e64 v231, v231, 0, s[18:19]
	v_fmac_f32_e32 v235, v100, v231
	v_cndmask_b32_e64 v232, v232, 0, s[44:45]
	v_fmac_f32_e32 v235, v101, v232
	v_cndmask_b32_e64 v233, v233, 0, s[46:47]
	v_fmac_f32_e32 v235, v102, v233
	v_cndmask_b32_e64 v234, v202, 0, s[48:49]
	v_fmac_f32_e32 v235, v103, v234
	v_mov_b32_e32 v202, v235
	s_nop 1
	v_permlane16_swap_b32_e32 v235, v202
	v_add_f32_e32 v235, v235, v202
	v_mov_b32_e32 v236, v235
	s_nop 1
	v_permlane32_swap_b32_e32 v235, v236
	s_and_saveexec_b64 s[86:87], s[8:9]
	s_cbranch_execz .LBB0_220
	v_add_f32_e32 v202, v235, v236
	ds_write_b32 v199, v202 offset:64
.LBB0_220:
	s_or_b64 exec, exec, s[86:87]
	v_mov_b32_e32 v202, v247
	s_nop 0
	v_sub_f32_e32 v235, v124, v202
	v_sub_f32_e32 v236, v125, v202
	v_mul_f32_e32 v235, 0x3fb8aa3b, v235
	v_sub_f32_e32 v237, v126, v202
	v_mul_f32_e32 v236, 0x3fb8aa3b, v236
	v_exp_f32_e32 v235, v235
	v_exp_f32_e32 v236, v236
	v_mul_f32_e32 v237, 0x3fb8aa3b, v237
	v_sub_f32_e32 v238, v127, v202
	v_exp_f32_e32 v237, v237
	v_mul_f32_e32 v238, 0x3fb8aa3b, v238
	v_sub_f32_e32 v239, v120, v202
	v_exp_f32_e32 v238, v238
	v_mul_f32_e32 v239, 0x3fb8aa3b, v239
	v_sub_f32_e32 v240, v121, v202
	v_cndmask_b32_e64 v235, v235, 0, s[50:51]
	v_exp_f32_e32 v239, v239
	v_mul_f32_e32 v240, 0x3fb8aa3b, v240
	v_sub_f32_e32 v241, v122, v202
	v_cndmask_b32_e64 v236, 0, v236, s[52:53]
	v_fma_f32 v243, v104, v235, 0
	v_exp_f32_e32 v240, v240
	v_mul_f32_e32 v241, 0x3fb8aa3b, v241
	v_sub_f32_e32 v202, v123, v202
	v_fmac_f32_e32 v243, v105, v236
	v_cndmask_b32_e64 v237, v237, 0, s[54:55]
	v_exp_f32_e32 v241, v241
	v_mul_f32_e32 v202, 0x3fb8aa3b, v202
	v_fmac_f32_e32 v243, v106, v237
	v_cndmask_b32_e64 v238, v238, 0, s[56:57]
	v_exp_f32_e32 v202, v202
	v_fmac_f32_e32 v243, v107, v238
	v_cndmask_b32_e64 v239, v239, 0, s[58:59]
	v_fmac_f32_e32 v243, v92, v239
	v_cndmask_b32_e64 v240, v240, 0, s[60:61]
	v_fmac_f32_e32 v243, v93, v240
	v_cndmask_b32_e64 v241, v241, 0, s[62:63]
	v_fmac_f32_e32 v243, v94, v241
	v_cndmask_b32_e64 v242, v202, 0, s[64:65]
	v_fmac_f32_e32 v243, v95, v242
	v_mov_b32_e32 v202, v243
	s_nop 1
	v_permlane16_swap_b32_e32 v243, v202
	v_add_f32_e32 v243, v243, v202
	v_mov_b32_e32 v244, v243
	s_nop 1
	v_permlane32_swap_b32_e32 v243, v244
	s_and_saveexec_b64 s[86:87], s[8:9]
	s_cbranch_execz .LBB0_222
	v_add_f32_e32 v202, v243, v244
	ds_write_b32 v199, v202 offset:128
.LBB0_222:
	s_or_b64 exec, exec, s[86:87]
	v_mov_b32_e32 v202, v248
	s_nop 0
	v_sub_f32_e32 v124, v124, v202
	v_sub_f32_e32 v125, v125, v202
	v_mul_f32_e32 v124, 0x3fb8aa3b, v124
	v_sub_f32_e32 v126, v126, v202
	v_mul_f32_e32 v125, 0x3fb8aa3b, v125
	v_exp_f32_e32 v124, v124
	v_exp_f32_e32 v125, v125
	v_mul_f32_e32 v126, 0x3fb8aa3b, v126
	v_sub_f32_e32 v127, v127, v202
	v_exp_f32_e32 v126, v126
	v_mul_f32_e32 v127, 0x3fb8aa3b, v127
	v_sub_f32_e32 v120, v120, v202
	v_exp_f32_e32 v127, v127
	v_mul_f32_e32 v120, 0x3fb8aa3b, v120
	v_sub_f32_e32 v121, v121, v202
	v_cndmask_b32_e64 v124, v124, 0, s[66:67]
	v_exp_f32_e32 v120, v120
	v_mul_f32_e32 v121, 0x3fb8aa3b, v121
	v_sub_f32_e32 v122, v122, v202
	v_cndmask_b32_e64 v125, 0, v125, s[68:69]
	v_fma_f32 v243, v96, v124, 0
	v_exp_f32_e32 v121, v121
	v_mul_f32_e32 v122, 0x3fb8aa3b, v122
	v_sub_f32_e32 v123, v123, v202
	v_fmac_f32_e32 v243, v97, v125
	v_cndmask_b32_e64 v126, v126, 0, s[70:71]
	v_exp_f32_e32 v122, v122
	v_mul_f32_e32 v123, 0x3fb8aa3b, v123
	v_fmac_f32_e32 v243, v98, v126
	v_cndmask_b32_e64 v127, v127, 0, s[72:73]
	v_exp_f32_e32 v123, v123
	v_fmac_f32_e32 v243, v99, v127
	v_cndmask_b32_e64 v120, v120, 0, s[74:75]
	v_fmac_f32_e32 v243, v88, v120
	v_cndmask_b32_e64 v121, v121, 0, s[76:77]
	v_fmac_f32_e32 v243, v89, v121
	v_cndmask_b32_e64 v122, v122, 0, s[78:79]
	v_fmac_f32_e32 v243, v90, v122
	v_cndmask_b32_e64 v123, v123, 0, s[80:81]
	v_fmac_f32_e32 v243, v91, v123
	v_mov_b32_e32 v202, v243
	s_nop 1
	v_permlane16_swap_b32_e32 v243, v202
	v_add_f32_e32 v243, v243, v202
	v_mov_b32_e32 v244, v243
	s_nop 1
	v_permlane32_swap_b32_e32 v243, v244
	s_and_saveexec_b64 s[86:87], s[8:9]
	s_cbranch_execz .LBB0_224
	v_add_f32_e32 v202, v243, v244
	ds_write_b32 v199, v202 offset:192

.LBB0_227:
	v_add_u32_e32 v89, s86, v214
	ds_read_b128 v[90:93], v89 offset:34816
	v_add_u32_e32 v94, s86, v212
	v_add_u32_e32 v95, 0x19800, v94
	v_add_u32_e32 v98, 0x1a900, v94
	ds_read_b128 v[94:97], v95
	ds_read_b128 v[98:101], v98
	v_add_u32_e32 v102, 0x11000, v89
	s_add_i32 s86, s86, 64
	s_cmpk_eq_i32 s86, 0x100
	s_waitcnt lgkmcnt(1)
	v_mfma_f32_16x16x32_bf16 v[84:87], v[90:93], v[94:97], v[84:87]
	s_waitcnt lgkmcnt(0)
	v_mfma_f32_16x16x32_bf16 v[80:83], v[90:93], v[98:101], v[80:83]
	ds_read_b128 v[90:93], v89 offset:39168
	v_add_u32_e32 v89, 0x12100, v89
	s_waitcnt lgkmcnt(0)
	v_mfma_f32_16x16x32_bf16 v[76:79], v[90:93], v[94:97], v[76:79]
	v_mfma_f32_16x16x32_bf16 v[72:75], v[90:93], v[98:101], v[72:75]
	ds_read_b128 v[90:93], v102
	s_waitcnt lgkmcnt(0)
	v_mfma_f32_16x16x32_bf16 v[56:59], v[90:93], v[94:97], v[56:59]
	v_mfma_f32_16x16x32_bf16 v[60:63], v[90:93], v[98:101], v[60:63]
	ds_read_b128 v[90:93], v89
	s_waitcnt lgkmcnt(0)
	v_mfma_f32_16x16x32_bf16 v[64:67], v[90:93], v[94:97], v[64:67]
	v_mfma_f32_16x16x32_bf16 v[68:71], v[90:93], v[98:101], v[68:71]
	s_cbranch_scc0 .LBB0_227
	ds_read_b128 v[90:93], v216
	ds_read_b128 v[94:97], v216 offset:16
	ds_read_b128 v[98:101], v216 offset:32
	ds_read_b128 v[102:105], v216 offset:48
	s_lshl_b32 s84, s84, 7
	s_sub_i32 s90, s94, s84
	s_and_b64 s[86:87], s[2:3], exec
	s_waitcnt lgkmcnt(3)
	v_lshlrev_b32_e32 v89, 16, v90
	v_and_b32_e32 v90, 0xffff0000, v90
	v_add_f32_e32 v89, v89, v90
	v_lshlrev_b32_e32 v90, 16, v91
	v_and_b32_e32 v91, 0xffff0000, v91
	v_add_f32_e32 v90, v90, v91
	v_add_f32_e32 v89, v89, v90
	v_lshlrev_b32_e32 v90, 16, v92
	v_and_b32_e32 v91, 0xffff0000, v92
	v_add_f32_e32 v90, v90, v91
	v_add_f32_e32 v89, v90, v89
	v_lshlrev_b32_e32 v90, 16, v93
	v_and_b32_e32 v91, 0xffff0000, v93
	v_add_f32_e32 v90, v90, v91
	v_add_f32_e32 v89, v90, v89
	s_waitcnt lgkmcnt(2)
	v_lshlrev_b32_e32 v90, 16, v94
	v_and_b32_e32 v91, 0xffff0000, v94
	v_add_f32_e32 v90, v90, v91
	v_lshlrev_b32_e32 v91, 16, v95
	v_and_b32_e32 v92, 0xffff0000, v95
	v_add_f32_e32 v91, v91, v92
	v_add_f32_e32 v90, v90, v91
	v_lshlrev_b32_e32 v91, 16, v96
	v_and_b32_e32 v92, 0xffff0000, v96
	v_add_f32_e32 v91, v91, v92
	v_add_f32_e32 v90, v91, v90
	v_lshlrev_b32_e32 v91, 16, v97
	v_and_b32_e32 v92, 0xffff0000, v97
	v_add_f32_e32 v91, v91, v92
	v_add_f32_e32 v89, 0, v89
	v_add_f32_e32 v90, v91, v90
	v_add_f32_e32 v89, v89, v90
	s_waitcnt lgkmcnt(1)
	v_lshlrev_b32_e32 v90, 16, v98
	v_and_b32_e32 v91, 0xffff0000, v98
	v_add_f32_e32 v90, v90, v91
	v_lshlrev_b32_e32 v91, 16, v99
	v_and_b32_e32 v92, 0xffff0000, v99
	v_add_f32_e32 v91, v91, v92
	v_add_f32_e32 v90, v90, v91
	v_lshlrev_b32_e32 v91, 16, v100
	v_and_b32_e32 v92, 0xffff0000, v100
	v_add_f32_e32 v91, v91, v92
	v_add_f32_e32 v90, v91, v90
	v_lshlrev_b32_e32 v91, 16, v101
	v_and_b32_e32 v92, 0xffff0000, v101
	v_add_f32_e32 v91, v91, v92
	v_add_f32_e32 v90, v91, v90
	v_add_f32_e32 v89, v89, v90
	s_waitcnt lgkmcnt(0)
	v_lshlrev_b32_e32 v90, 16, v102
	v_and_b32_e32 v91, 0xffff0000, v102
	v_add_f32_e32 v90, v90, v91
	v_lshlrev_b32_e32 v91, 16, v103
	v_and_b32_e32 v92, 0xffff0000, v103
	v_add_f32_e32 v91, v91, v92
	v_add_f32_e32 v90, v90, v91
	v_lshlrev_b32_e32 v91, 16, v104
	v_and_b32_e32 v92, 0xffff0000, v104
	v_add_f32_e32 v91, v91, v92
	v_add_f32_e32 v90, v91, v90
	v_lshlrev_b32_e32 v91, 16, v105
	v_and_b32_e32 v92, 0xffff0000, v105
	v_add_f32_e32 v91, v91, v92
	s_cselect_b32 s84, s84, s90
	ds_read_b128 v[92:95], v182
	s_add_i32 s84, s84, s89
	v_or_b32_e32 v96, s84, v200
	v_ashrrev_i32_e32 v97, 31, v96
	v_lshlrev_b64 v[96:97], 11, v[96:97]
	v_lshl_add_u64 v[100:101], v[146:147], 0, v[96:97]
	ds_read_b128 v[96:99], v182 offset:64
	s_waitcnt lgkmcnt(1)
	v_mul_f32_e32 v84, v84, v92
	v_mul_f32_e32 v80, v80, v92
	v_cvt_pk_bf16_f32 v84, v84, v84
	global_store_short v[100:101], v84, off
	v_cvt_pk_bf16_f32 v80, v80, v80
	global_store_short v[100:101], v80, off offset:32
	v_or_b32_e32 v100, s84, v201
	v_ashrrev_i32_e32 v101, 31, v100
	v_lshlrev_b64 v[100:101], 11, v[100:101]
	v_mul_f32_e32 v80, v85, v93
	v_lshl_add_u64 v[100:101], v[146:147], 0, v[100:101]
	v_cvt_pk_bf16_f32 v80, v80, v80
	global_store_short v[100:101], v80, off
	v_mul_f32_e32 v80, v81, v93
	v_cvt_pk_bf16_f32 v80, v80, v80
	global_store_short v[100:101], v80, off offset:32
	v_or_b32_e32 v80, s84, v203
	v_ashrrev_i32_e32 v81, 31, v80
	v_lshlrev_b64 v[80:81], 11, v[80:81]
	v_lshl_add_u64 v[80:81], v[146:147], 0, v[80:81]
	v_mul_f32_e32 v84, v86, v94
	v_mul_f32_e32 v82, v82, v94
	v_cvt_pk_bf16_f32 v84, v84, v84
	global_store_short v[80:81], v84, off
	v_cvt_pk_bf16_f32 v82, v82, v82
	global_store_short v[80:81], v82, off offset:32
	v_or_b32_e32 v80, s84, v204
	v_ashrrev_i32_e32 v81, 31, v80
	v_lshlrev_b64 v[80:81], 11, v[80:81]
	v_mul_f32_e32 v82, v87, v95
	v_lshl_add_u64 v[80:81], v[146:147], 0, v[80:81]
	v_cvt_pk_bf16_f32 v82, v82, v82
	global_store_short v[80:81], v82, off
	v_mul_f32_e32 v82, v83, v95
	v_cvt_pk_bf16_f32 v82, v82, v82
	global_store_short v[80:81], v82, off offset:32
	v_or_b32_e32 v80, s84, v205
	v_ashrrev_i32_e32 v81, 31, v80
	v_lshlrev_b64 v[80:81], 11, v[80:81]
	v_lshl_add_u64 v[80:81], v[146:147], 0, v[80:81]
	s_waitcnt lgkmcnt(0)
	v_mul_f32_e32 v76, v76, v96
	v_mul_f32_e32 v72, v72, v96
	v_cvt_pk_bf16_f32 v76, v76, v76
	global_store_short v[80:81], v76, off
	v_cvt_pk_bf16_f32 v72, v72, v72
	global_store_short v[80:81], v72, off offset:32
	v_or_b32_e32 v80, s84, v206
	v_ashrrev_i32_e32 v81, 31, v80
	v_lshlrev_b64 v[80:81], 11, v[80:81]
	v_mul_f32_e32 v72, v77, v97
	v_add_f32_e32 v90, v91, v90
	v_lshl_add_u64 v[80:81], v[146:147], 0, v[80:81]
	v_cvt_pk_bf16_f32 v72, v72, v72
	v_add_f32_e32 v89, v89, v90
	global_store_short v[80:81], v72, off
	v_mul_f32_e32 v72, v73, v97
	s_nop 1
	v_add_f32_dpp v89, v89, v89 quad_perm:[1,0,3,2] row_mask:0xf bank_mask:0xf
	v_cvt_pk_bf16_f32 v72, v72, v72
	global_store_short v[80:81], v72, off offset:32
	v_or_b32_e32 v72, s84, v207
	v_ashrrev_i32_e32 v73, 31, v72
	v_lshlrev_b64 v[72:73], 11, v[72:73]
	v_lshl_add_u64 v[72:73], v[146:147], 0, v[72:73]
	v_mul_f32_e32 v76, v78, v98
	v_mul_f32_e32 v74, v74, v98
	s_waitcnt lgkmcnt(0)
	s_nop 0
	v_cvt_pk_bf16_f32 v76, v76, v76
	global_store_short v[72:73], v76, off
	v_cvt_pk_bf16_f32 v74, v74, v74
	global_store_short v[72:73], v74, off offset:32
	v_or_b32_e32 v72, s84, v208
	v_mov_b32_dpp v90, v89 quad_perm:[2,3,0,1] row_mask:0xf bank_mask:0xf
	v_ashrrev_i32_e32 v73, 31, v72
	v_lshlrev_b64 v[72:73], 11, v[72:73]
	v_mul_f32_e32 v74, v79, v99
	v_lshl_add_u64 v[72:73], v[146:147], 0, v[72:73]
	v_cvt_pk_bf16_f32 v74, v74, v74
	global_store_short v[72:73], v74, off
	v_mul_f32_e32 v74, v75, v99
	v_cvt_pk_bf16_f32 v76, v64, v65
	v_cvt_pk_bf16_f32 v74, v74, v74
	global_store_short v[72:73], v74, off offset:32
	s_waitcnt lgkmcnt(0)
	s_barrier
	v_cvt_pk_bf16_f32 v72, v56, v57
	v_cvt_pk_bf16_f32 v73, v58, v59
	v_cvt_pk_bf16_f32 v77, v66, v67
	ds_write2_b64 v217, v[72:73], v[76:77] offset1:4
	v_add_u32_e32 v76, 0x1000, v217
	v_cvt_pk_bf16_f32 v74, v60, v61
	v_cvt_pk_bf16_f32 v75, v62, v63
	v_cvt_pk_bf16_f32 v72, v68, v69
	v_cvt_pk_bf16_f32 v73, v70, v71
	ds_write2_b64 v76, v[74:75], v[72:73] offset0:32 offset1:36
	s_and_saveexec_b64 s[86:87], s[6:7]
	s_cbranch_execz .LBB0_201
	ds_read_b32 v73, v134
	v_add_f32_e32 v72, v89, v90
	s_waitcnt lgkmcnt(0)
	v_fmac_f32_e32 v72, v88, v73
	ds_write_b32 v134, v72
	s_branch .LBB0_201
